# ssd_states chunk-state stores widened: 16 dwordx2 -> 8 dwordx4 per wave and head group via v_permlane16_swap
# speedup vs baseline: 1.0069x; 1.0069x over previous
.LBB0_778:
	v_add_u32_e32 v2, s13, v114
	v_add_u32_e32 v75, s13, v111
	ds_read2_b64 v[86:89], v2 offset1:1
	ds_read2_b64 v[90:93], v75 offset1:1
	v_add_u32_e32 v75, 0x1080, v75
	ds_read2_b64 v[94:97], v75 offset1:1
	v_add_u32_e32 v71, s13, v113
	v_add_u32_e32 v73, s13, v112
	v_add_u32_e32 v77, 0x5280, v2
	s_waitcnt lgkmcnt(1)
	v_mfma_f32_16x16x32_bf16 v[64:67], v[86:89], v[90:93], v[64:67]
	ds_read2_b64 v[98:101], v73 offset1:1
	ds_read2_b64 v[118:121], v77 offset1:1
	v_add_u32_e32 v73, 0x2100, v2
	s_waitcnt lgkmcnt(2)
	v_mfma_f32_16x16x32_bf16 v[32:35], v[86:89], v[94:97], v[32:35]
	ds_read2_b64 v[86:89], v71 offset1:1
	v_add_u32_e32 v71, 0x1080, v2
	v_add_u32_e32 v75, 0x4200, v2
	v_add_u32_e32 v2, 0x6300, v2
	s_waitcnt lgkmcnt(0)
	v_mfma_f32_16x16x32_bf16 v[52:55], v[86:89], v[90:93], v[52:55]
	ds_read2_b64 v[102:105], v75 offset1:1
	ds_read2_b64 v[122:125], v2 offset1:1
	s_add_i32 s13, s13, 64
	v_mfma_f32_16x16x32_bf16 v[36:39], v[98:101], v[90:93], v[36:39]
	s_cmpk_eq_i32 s13, 0x100
	v_mfma_f32_16x16x32_bf16 v[12:15], v[86:89], v[94:97], v[12:15]
	ds_read2_b64 v[86:89], v71 offset1:1
	v_mfma_f32_16x16x32_bf16 v[20:23], v[98:101], v[94:97], v[20:23]
	ds_read2_b64 v[98:101], v73 offset1:1
	s_waitcnt lgkmcnt(1)
	v_mfma_f32_16x16x32_bf16 v[60:63], v[86:89], v[90:93], v[60:63]
	s_waitcnt lgkmcnt(0)
	v_mfma_f32_16x16x32_bf16 v[56:59], v[98:101], v[90:93], v[56:59]
	v_mfma_f32_16x16x32_bf16 v[48:51], v[102:105], v[90:93], v[48:51]
	v_mfma_f32_16x16x32_bf16 v[44:47], v[118:121], v[90:93], v[44:47]
	v_mfma_f32_16x16x32_bf16 v[40:43], v[122:125], v[90:93], v[40:43]
	v_mfma_f32_16x16x32_bf16 v[24:27], v[86:89], v[94:97], v[24:27]
	v_mfma_f32_16x16x32_bf16 v[16:19], v[98:101], v[94:97], v[16:19]
	v_mfma_f32_16x16x32_bf16 v[8:11], v[102:105], v[94:97], v[8:11]
	v_mfma_f32_16x16x32_bf16 v[4:7], v[118:121], v[94:97], v[4:7]
	v_mfma_f32_16x16x32_bf16 v[28:31], v[122:125], v[94:97], v[28:31]
	s_cbranch_scc0 .LBB0_778
	v_add_u32_e32 v86, s12, v110
	v_ashrrev_i32_e32 v87, 31, v86
	v_lshlrev_b64 v[86:87], 14, v[86:87]
	v_lshl_add_u64 v[86:87], v[68:69], 0, v[86:87]
	v_bfe_u32 v88, v159, 4, 1
	v_mul_u32_u24_e32 v88, 24, v88
	v_add_u32_e32 v88, v88, v70
	v_mov_b32_e32 v89, v3
	s_mov_b64 s[12:13], 0x1000
	v_lshl_add_u64 v[90:91], v[86:87], 0, v[88:89]
	v_lshl_add_u64 v[92:93], v[90:91], 0, s[12:13]
	s_add_i32 s8, s8, 1
	v_cvt_pk_bf16_f32 v64, v64, v65
	v_cvt_pk_bf16_f32 v65, v66, v67
	v_cvt_pk_bf16_f32 v66, v60, v61
	v_cvt_pk_bf16_f32 v67, v62, v63
	v_cvt_pk_bf16_f32 v56, v56, v57
	v_cvt_pk_bf16_f32 v57, v58, v59
	v_cvt_pk_bf16_f32 v58, v52, v53
	v_cvt_pk_bf16_f32 v59, v54, v55
	v_cvt_pk_bf16_f32 v48, v48, v49
	v_cvt_pk_bf16_f32 v49, v50, v51
	v_cvt_pk_bf16_f32 v50, v44, v45
	v_cvt_pk_bf16_f32 v51, v46, v47
	v_cvt_pk_bf16_f32 v40, v40, v41
	v_cvt_pk_bf16_f32 v41, v42, v43
	v_cvt_pk_bf16_f32 v42, v36, v37
	v_cvt_pk_bf16_f32 v43, v38, v39
	v_cvt_pk_bf16_f32 v32, v32, v33
	v_cvt_pk_bf16_f32 v33, v34, v35
	v_cvt_pk_bf16_f32 v34, v24, v25
	v_cvt_pk_bf16_f32 v35, v26, v27
	v_cvt_pk_bf16_f32 v16, v16, v17
	v_cvt_pk_bf16_f32 v17, v18, v19
	v_cvt_pk_bf16_f32 v18, v12, v13
	v_cvt_pk_bf16_f32 v19, v14, v15
	v_cvt_pk_bf16_f32 v8, v8, v9
	v_cvt_pk_bf16_f32 v9, v10, v11
	v_cvt_pk_bf16_f32 v10, v4, v5
	v_cvt_pk_bf16_f32 v11, v6, v7
	v_cvt_pk_bf16_f32 v28, v28, v29
	v_cvt_pk_bf16_f32 v29, v30, v31
	v_cvt_pk_bf16_f32 v30, v20, v21
	v_cvt_pk_bf16_f32 v31, v22, v23
	s_nop 1
	v_permlane16_swap_b32_e32 v64, v66
	v_permlane16_swap_b32_e32 v65, v67
	v_permlane16_swap_b32_e32 v56, v58
	v_permlane16_swap_b32_e32 v57, v59
	v_permlane16_swap_b32_e32 v48, v50
	v_permlane16_swap_b32_e32 v49, v51
	v_permlane16_swap_b32_e32 v40, v42
	v_permlane16_swap_b32_e32 v41, v43
	v_permlane16_swap_b32_e32 v32, v34
	v_permlane16_swap_b32_e32 v33, v35
	v_permlane16_swap_b32_e32 v16, v18
	v_permlane16_swap_b32_e32 v17, v19
	v_permlane16_swap_b32_e32 v8, v10
	v_permlane16_swap_b32_e32 v9, v11
	v_permlane16_swap_b32_e32 v28, v30
	v_permlane16_swap_b32_e32 v29, v31
	s_cmp_eq_u32 s8, 4
	global_store_dwordx4 v[90:91], v[64:67], off
	global_store_dwordx4 v[90:91], v[56:59], off offset:64
	global_store_dwordx4 v[90:91], v[48:51], off offset:128
	global_store_dwordx4 v[90:91], v[40:43], off offset:192
	global_store_dwordx4 v[92:93], v[32:35], off
	global_store_dwordx4 v[92:93], v[16:19], off offset:64
	global_store_dwordx4 v[92:93], v[8:11], off offset:128
	global_store_dwordx4 v[92:93], v[28:31], off offset:192
	s_barrier
	s_cbranch_scc0 .LBB0_768
	s_branch .LBB0_676
